# v46 + O3 pooling-difference jobs dealt 3 per block to blocks with four GEMM tiles and 7 to the others (ckv-state jobs unchanged)
# baseline (speedup 1.0000x reference)
.LBB0_446:
	s_cmpk_lg_u32 s38, 0x100
	s_cbranch_scc1 .Lo3_orig
	s_cmpk_ge_i32 s8, 0x940
	s_cbranch_scc1 .Lo3_orig
	s_cmpk_ge_i32 s8, 0x340
	s_cbranch_scc1 .Lo3_pool
	s_add_i32 s8, s8, 0x100
	s_cmpk_lt_i32 s8, 0x340
	s_cbranch_scc1 .LBB0_447
	s_movk_i32 s0, 0x340
	s_movk_i32 s1, 0x3c0
	s_cmpk_ge_u32 s92, 0x40
	s_cselect_b32 s0, s1, s0
	s_add_i32 s8, s0, s92
	s_branch .LBB0_447
.Lo3_pool:
	s_movk_i32 s0, 0x40
	s_movk_i32 s1, 0xc0
	s_cmpk_ge_u32 s92, 0x40
	s_cselect_b32 s0, s1, s0
	s_add_i32 s8, s8, s0
	s_movk_i32 s0, 0x400
	s_movk_i32 s1, 0x940
	s_cmpk_ge_u32 s92, 0x40
	s_cselect_b32 s0, s1, s0
	s_cmp_lt_i32 s8, s0
	s_cbranch_scc1 .LBB0_447
	s_add_i32 s8, s92, 0x940
	s_branch .LBB0_447
